# MLA attention loops: row-max chain and threshold test only on a wave's first tile; later tiles rescale after the tile when the tile's exponential sum exceeds 2^20 (same deferred-max softmax, different
# speedup vs baseline: 1.0150x; 1.0150x over previous
.LBB0_1198:
	s_abs_i32 s8, s51
	s_mul_hi_u32 s9, s8, s30
	s_mul_i32 s10, s9, s29
	s_ashr_i32 s2, s51, 31
	s_sub_i32 s8, s8, s10
	s_xor_b32 s2, s2, s26
	s_add_i32 s10, s9, 1
	s_sub_i32 s11, s8, s29
	s_cmp_ge_u32 s8, s29
	s_cselect_b32 s9, s10, s9
	s_cselect_b32 s8, s11, s8
	s_add_i32 s10, s9, 1
	s_cmp_ge_u32 s8, s29
	s_cselect_b32 s8, s10, s9
	s_xor_b32 s8, s8, s2
	s_sub_i32 s2, s8, s2
	s_mul_i32 s8, s2, s42
	s_sub_i32 s24, s51, s8
	s_ashr_i32 s25, s24, 31
	s_lshr_b32 s8, s25, 26
	s_add_i32 s8, s24, s8
	s_ashr_i32 s9, s8, 6
	s_and_b32 s10, s8, 0xffffffc0
	s_not_b32 s52, s9
	s_sub_i32 s8, s24, s10
	s_and_b32 s11, s2, 1
	s_add_i32 s52, s27, s52
	s_cmp_eq_u32 s11, 0
	s_cselect_b32 s9, s9, s52
	s_mul_i32 s2, s2, s27
	s_add_i32 s9, s9, s2
	s_lshl_b32 s2, s9, 8
	s_sub_i32 s11, s28, s2
	s_add_i32 s52, s11, 0xf00
	s_ashr_i32 s9, s8, 31
	s_mul_i32 s58, s8, 0x180000
	s_mul_hi_i32 s53, s8, 0x180000
	s_add_u32 s54, s4, s58
	s_addc_u32 s55, s5, s53
	v_or_b32_e32 v1, s52, v179
	v_mov_b64_e32 v[2:3], s[54:55]
	v_mad_i64_i32 v[2:3], s[54:55], v1, s31, v[2:3]
	v_lshl_add_u64 v[2:3], v[2:3], 0, v[166:167]
	v_mov_b32_e32 v1, v178
	global_load_dwordx4 v[118:121], v[2:3], off
	global_load_dwordx4 v[122:125], v[2:3], off offset:32
	global_load_dwordx4 v[126:129], v[2:3], off offset:64
	global_load_dwordx4 v[130:133], v[2:3], off offset:96
	global_load_dwordx4 v[134:137], v[2:3], off offset:128
	global_load_dwordx4 v[138:141], v[2:3], off offset:160
	global_load_dwordx4 v[142:145], v[2:3], off offset:192
	global_load_dwordx4 v[146:149], v[2:3], off offset:224
	global_load_dwordx4 v[150:153], v[2:3], off offset:256
	global_load_dwordx4 v[154:157], v[2:3], off offset:288
	global_load_dwordx4 v[158:161], v[2:3], off offset:320
	global_load_dwordx4 v[162:165], v[2:3], off offset:352
	s_lshl_b64 s[56:57], s[8:9], 20
	v_add_u32_e32 v185, s70, v1
	v_ashrrev_i32_e32 v4, 31, v185
	v_lshrrev_b32_e32 v4, 28, v4
	s_add_u32 s54, s6, s58
	v_lshlrev_b32_e32 v168, 3, v185
	v_add_u32_e32 v5, v185, v4
	s_addc_u32 s55, s7, s53
	v_ashrrev_i32_e32 v169, 31, v168
	v_ashrrev_i32_e32 v4, 4, v5
	v_and_b32_e32 v5, 0x1ffffff0, v5
	v_lshl_add_u64 v[2:3], v[168:169], 1, s[54:55]
	v_sub_u32_e32 v5, v185, v5
	s_add_u32 s56, s12, s56
	v_lshlrev_b32_e32 v170, 3, v5
	v_ashrrev_i32_e32 v5, 31, v4
	v_add_co_u32_e32 v8, vcc, s34, v2
	s_addc_u32 s57, s13, s57
	v_lshlrev_b64 v[172:173], 8, v[4:5]
	v_addc_co_u32_e32 v9, vcc, 0, v3, vcc
	v_lshl_add_u64 v[6:7], s[56:57], 0, v[172:173]
	v_ashrrev_i32_e32 v171, 31, v170
	global_load_dwordx4 v[98:101], v[2:3], off
	v_add_co_u32_e32 v2, vcc, s35, v2
	v_lshl_add_u64 v[6:7], v[170:171], 1, v[6:7]
	s_nop 0
	v_addc_co_u32_e32 v3, vcc, 0, v3, vcc
	global_load_dwordx4 v[102:105], v[8:9], off
	global_load_dwordx4 v[106:109], v[2:3], off
	global_load_dwordx4 v[110:113], v[6:7], off
	v_add_co_u32_e32 v2, vcc, s34, v6
	s_sub_i32 s2, 0x103f, s2
	s_nop 0
	v_addc_co_u32_e32 v3, vcc, 0, v7, vcc
	global_load_dwordx4 v[114:117], v[2:3], off
	s_ashr_i32 s9, s2, 31
	s_lshr_b32 s9, s9, 26
	s_add_i32 s2, s2, s9
	s_ashr_i32 s9, s2, 6
	s_add_i32 s2, s11, 0xf1f
	s_ashr_i32 s11, s2, 31
	s_lshr_b32 s11, s11, 26
	s_add_i32 s2, s2, s11
	s_ashr_i32 s2, s2, 6
	s_add_i32 s2, s2, 1
	s_min_i32 s2, s2, s9
	v_mul_hi_i32 v2, v185, s36
	v_add_u32_e32 v188, 0x200, v185
	v_add_u32_e32 v187, 0x400, v185
	s_cmp_lt_i32 s2, 1
	v_mul_lo_u32 v183, v4, s39
	s_mul_hi_i32 s53, s10, 0x180000
	s_mul_i32 s54, s10, 0x180000
	v_lshrrev_b32_e32 v191, 31, v2
	v_ashrrev_i32_e32 v192, 2, v2
	v_mul_hi_i32 v190, v188, s36
	v_mul_hi_i32 v189, v187, s36
	v_lshlrev_b32_e32 v184, 1, v170
	s_waitcnt vmcnt(63) expcnt(7) lgkmcnt(15)
	s_barrier
	s_cbranch_scc1 .LBB0_1208
	v_bfe_u32 v2, v1, 5, 1
	v_and_b32_e32 v3, 31, v1
	s_lshl_b64 s[56:57], s[24:25], 20
	v_or_b32_e32 v193, s52, v3
	v_lshlrev_b32_e32 v194, 2, v2
	v_lshrrev_b32_e32 v4, 2, v1
	v_and_b32_e32 v16, 16, v1
	v_lshlrev_b32_e32 v1, 2, v1
	v_mul_u32_u24_e32 v18, 0xc8, v3
	v_lshlrev_b32_e32 v202, 4, v2
	v_lshl_add_u64 v[2:3], s[56:57], 0, v[172:173]
	s_ashr_i32 s11, s10, 31
	v_and_b32_e32 v17, 12, v1
	v_add_u32_e32 v1, v192, v191
	v_lshl_add_u64 v[2:3], v[170:171], 1, v[2:3]
	s_lshl_b64 s[56:57], s[10:11], 20
	v_mul_lo_u32 v5, v1, s37
	v_mul_lo_u32 v195, v1, s38
	v_mov_b32_e32 v1, s57
	v_subrev_co_u32_e32 v2, vcc, s56, v2
	v_lshrrev_b32_e32 v6, 31, v190
	s_nop 0
	v_subb_co_u32_e32 v3, vcc, v3, v1, vcc
	v_lshl_add_u64 v[174:175], s[16:17], 0, v[2:3]
	v_lshlrev_b64 v[2:3], 1, v[168:169]
	v_ashrrev_i32_e32 v7, 2, v190
	v_lshrrev_b32_e32 v8, 31, v189
	v_ashrrev_i32_e32 v9, 2, v189
	v_mad_i64_i32 v[2:3], s[56:57], s24, v181, v[2:3]
	v_add_u32_e32 v6, v7, v6
	v_add_u32_e32 v8, v9, v8
	v_mov_b32_e32 v1, s53
	v_subrev_co_u32_e32 v2, vcc, s54, v2
	v_and_or_b32 v4, v4, 3, v194
	v_mul_lo_u32 v7, v6, s37
	v_mul_lo_u32 v9, v8, s37
	v_subb_co_u32_e32 v3, vcc, v3, v1, vcc
	v_mov_b32_e32 v14, v0
	v_mov_b32_e32 v15, v0
	v_add_lshl_u32 v196, v5, v185, 4
	v_mul_lo_u32 v197, v6, s38
	v_add_lshl_u32 v198, v7, v188, 4
	v_mul_lo_u32 v199, v8, s38
	v_add_lshl_u32 v200, v9, v187, 4
	v_mul_u32_u24_e32 v201, 0x140, v4
	v_lshl_add_u64 v[176:177], s[20:21], 0, v[2:3]
	v_mov_b32_e32 v1, v0
	v_mov_b32_e32 v2, v0
	v_mov_b32_e32 v3, v0
	v_mov_b32_e32 v4, v0
	v_mov_b32_e32 v5, v0
	v_mov_b32_e32 v6, v0
	v_mov_b32_e32 v7, v0
	v_mov_b32_e32 v8, v0
	v_mov_b32_e32 v9, v0
	v_mov_b32_e32 v10, v0
	v_mov_b32_e32 v11, v0
	v_mov_b32_e32 v12, v0
	v_mov_b32_e32 v13, v0
	v_lshlrev_b32_e32 v203, 1, v18
	v_mov_b64_e32 v[48:49], v[14:15]
	v_mov_b64_e32 v[64:65], v[14:15]
	v_mov_b64_e32 v[32:33], v[14:15]
	v_lshlrev_b32_e32 v204, 1, v16
	v_lshlrev_b32_e32 v205, 1, v17
	v_mov_b64_e32 v[46:47], v[12:13]
	v_mov_b64_e32 v[44:45], v[10:11]
	v_mov_b64_e32 v[42:43], v[8:9]
	v_mov_b64_e32 v[40:41], v[6:7]
	v_mov_b64_e32 v[38:39], v[4:5]
	v_mov_b64_e32 v[36:37], v[2:3]
	v_mov_b64_e32 v[34:35], v[0:1]
	v_mov_b64_e32 v[62:63], v[12:13]
	v_mov_b64_e32 v[60:61], v[10:11]
	v_mov_b64_e32 v[58:59], v[8:9]
	v_mov_b64_e32 v[56:57], v[6:7]
	v_mov_b64_e32 v[54:55], v[4:5]
	v_mov_b64_e32 v[52:53], v[2:3]
	v_mov_b64_e32 v[50:51], v[0:1]
	v_mov_b64_e32 v[30:31], v[12:13]
	v_mov_b64_e32 v[28:29], v[10:11]
	v_mov_b64_e32 v[26:27], v[8:9]
	v_mov_b64_e32 v[24:25], v[6:7]
	v_mov_b64_e32 v[22:23], v[4:5]
	v_mov_b64_e32 v[20:21], v[2:3]
	v_mov_b64_e32 v[18:19], v[0:1]
	v_mov_b64_e32 v[16:17], v[14:15]
	s_mov_b32 s11, 0
	v_mov_b32_e32 v186, 0
	v_mov_b32_e32 v206, 0xf149f2ca
	s_mov_b32 s98, 1
	v_mov_b32_e32 v232, 0
	v_mov_b32_e32 v233, 0
	v_mov_b32_e32 v234, 0
	v_mov_b32_e32 v235, 0
	v_mov_b32_e32 v236, 0
	v_mov_b32_e32 v237, 0
	v_mov_b32_e32 v238, 0
	v_mov_b32_e32 v239, 0
	v_mov_b32_e32 v240, 0
	v_mov_b32_e32 v241, 0
	v_mov_b32_e32 v242, 0
	v_mov_b32_e32 v243, 0
	v_mov_b32_e32 v244, 0
	v_mov_b32_e32 v245, 0
	v_mov_b32_e32 v246, 0
	v_mov_b32_e32 v247, 0
	v_mov_b32_e32 v248, 0
	v_mov_b32_e32 v249, v206
	s_mov_b32 s55, 63
	v_mov_b64_e32 v[14:15], v[12:13]
	v_mov_b64_e32 v[12:13], v[10:11]
	v_mov_b64_e32 v[10:11], v[8:9]
	v_mov_b64_e32 v[8:9], v[6:7]
	v_mov_b64_e32 v[6:7], v[4:5]
	v_mov_b64_e32 v[4:5], v[2:3]
	v_mov_b64_e32 v[2:3], v[0:1]
	s_branch .LBB0_1201
.LBB0_1200:
	v_exp_f32_e32 v207, v82
	v_exp_f32_e32 v208, v83
	v_exp_f32_e32 v209, v84
	v_add_u32_e32 v1, s56, v201
	v_exp_f32_e32 v211, v86
	v_add3_u32 v1, v1, v204, v205
	v_exp_f32_e32 v224, v88
	v_exp_f32_e32 v226, v87
	v_exp_f32_e32 v225, v89
	v_exp_f32_e32 v227, v85
	ds_read_b64_tr_b16 v[86:87], v1 offset:25600
	ds_read_b64_tr_b16 v[88:89], v1 offset:28160
	v_cvt_pk_bf16_f32 v84, v211, v226
	v_cvt_pk_bf16_f32 v85, v224, v225
	v_cvt_pk_bf16_f32 v83, v209, v227
	v_cvt_pk_bf16_f32 v82, v207, v208
	ds_read_b64_tr_b16 v[212:213], v1 offset:25664
	ds_read_b64_tr_b16 v[216:217], v1 offset:25728
	ds_read_b64_tr_b16 v[220:221], v1 offset:25792
	ds_read_b64_tr_b16 v[214:215], v1 offset:28224
	ds_read_b64_tr_b16 v[218:219], v1 offset:28288
	ds_read_b64_tr_b16 v[222:223], v1 offset:28352
	s_waitcnt lgkmcnt(6)
	v_mfma_f32_32x32x16_bf16 v[50:65], v[86:89], v[82:85], v[50:65]
	v_exp_f32_e32 v228, v90
	v_exp_f32_e32 v229, v91
	v_exp_f32_e32 v230, v92
	v_exp_f32_e32 v231, v94
	s_waitcnt lgkmcnt(1)
	v_mfma_f32_32x32x16_bf16 v[18:33], v[216:219], v[82:85], v[18:33]
	v_exp_f32_e32 v216, v96
	v_exp_f32_e32 v217, v97
	v_exp_f32_e32 v218, v95
	v_exp_f32_e32 v219, v93
	ds_read_b64_tr_b16 v[86:87], v1 offset:30720
	ds_read_b64_tr_b16 v[88:89], v1 offset:33280
	v_add_f32_e32 v207, 0, v207
	v_mfma_f32_32x32x16_bf16 v[34:49], v[212:215], v[82:85], v[34:49]
	ds_read_b64_tr_b16 v[90:91], v1 offset:30784
	ds_read_b64_tr_b16 v[94:95], v1 offset:30848
	ds_read_b64_tr_b16 v[212:213], v1 offset:30912
	ds_read_b64_tr_b16 v[92:93], v1 offset:33344
	ds_read_b64_tr_b16 v[96:97], v1 offset:33408
	ds_read_b64_tr_b16 v[214:215], v1 offset:33472
	s_add_i32 s55, s55, 64
	v_lshl_add_u64 v[174:175], v[174:175], 0, s[14:15]
	s_cmp_eq_u32 s2, s11
	v_lshl_add_u64 v[176:177], v[176:177], 0, s[18:19]
	s_waitcnt lgkmcnt(8)
	v_mfma_f32_32x32x16_bf16 v[2:17], v[220:223], v[82:85], v[2:17]
	v_cvt_pk_bf16_f32 v85, v216, v217
	v_cvt_pk_bf16_f32 v84, v231, v218
	v_cvt_pk_bf16_f32 v83, v230, v219
	v_cvt_pk_bf16_f32 v82, v228, v229
	s_waitcnt lgkmcnt(6)
	s_nop 0
	v_mfma_f32_32x32x16_bf16 v[50:65], v[86:89], v[82:85], v[50:65]
	v_add_f32_e32 v86, v208, v207
	v_add_f32_e32 v86, v209, v86
	v_exp_f32_e32 v208, v66
	v_add_f32_e32 v86, v227, v86
	v_exp_f32_e32 v209, v67
	v_add_f32_e32 v86, v211, v86
	v_exp_f32_e32 v211, v68
	v_exp_f32_e32 v220, v70
	s_waitcnt lgkmcnt(1)
	v_mfma_f32_32x32x16_bf16 v[18:33], v[94:97], v[82:85], v[18:33]
	v_exp_f32_e32 v94, v72
	v_exp_f32_e32 v95, v73
	v_exp_f32_e32 v96, v71
	v_exp_f32_e32 v97, v69
	ds_read_b64_tr_b16 v[70:71], v1 offset:35840
	ds_read_b64_tr_b16 v[72:73], v1 offset:38400
	v_add_f32_e32 v207, v226, v86
	v_cvt_pk_bf16_f32 v69, v94, v95
	v_cvt_pk_bf16_f32 v68, v220, v96
	v_cvt_pk_bf16_f32 v67, v211, v97
	v_cvt_pk_bf16_f32 v66, v208, v209
	v_mfma_f32_32x32x16_bf16 v[34:49], v[90:93], v[82:85], v[34:49]
	s_waitcnt lgkmcnt(0)
	v_mfma_f32_32x32x16_bf16 v[50:65], v[70:73], v[66:69], v[50:65]
	v_add_f32_e32 v70, v224, v207
	v_add_f32_e32 v70, v225, v70
	v_add_f32_e32 v70, v228, v70
	v_add_f32_e32 v70, v229, v70
	v_add_f32_e32 v207, v230, v70
	v_mfma_f32_32x32x16_bf16 v[2:17], v[212:215], v[82:85], v[2:17]
	ds_read_b64_tr_b16 v[82:83], v1 offset:35904
	ds_read_b64_tr_b16 v[86:87], v1 offset:35968
	ds_read_b64_tr_b16 v[90:91], v1 offset:36032
	ds_read_b64_tr_b16 v[84:85], v1 offset:38464
	ds_read_b64_tr_b16 v[88:89], v1 offset:38528
	ds_read_b64_tr_b16 v[92:93], v1 offset:38592
	v_exp_f32_e32 v212, v74
	v_exp_f32_e32 v213, v75
	v_exp_f32_e32 v214, v76
	v_exp_f32_e32 v215, v78
	s_waitcnt lgkmcnt(1)
	v_mfma_f32_32x32x16_bf16 v[18:33], v[86:89], v[66:69], v[18:33]
	v_exp_f32_e32 v86, v80
	v_exp_f32_e32 v87, v81
	v_exp_f32_e32 v88, v79
	v_exp_f32_e32 v89, v77
	ds_read_b64_tr_b16 v[70:71], v1 offset:40960
	ds_read_b64_tr_b16 v[72:73], v1 offset:43520
	v_mfma_f32_32x32x16_bf16 v[34:49], v[82:85], v[66:69], v[34:49]
	ds_read_b64_tr_b16 v[74:75], v1 offset:41024
	ds_read_b64_tr_b16 v[78:79], v1 offset:41088
	ds_read_b64_tr_b16 v[82:83], v1 offset:41152
	ds_read_b64_tr_b16 v[76:77], v1 offset:43584
	ds_read_b64_tr_b16 v[80:81], v1 offset:43648
	ds_read_b64_tr_b16 v[84:85], v1 offset:43712
	v_add_f32_e32 v1, v219, v207
	v_add_f32_e32 v1, v231, v1
	v_add_f32_e32 v1, v218, v1
	v_add_f32_e32 v1, v216, v1
	v_add_f32_e32 v1, v217, v1
	v_add_f32_e32 v1, v208, v1
	s_waitcnt lgkmcnt(8)
	v_mfma_f32_32x32x16_bf16 v[2:17], v[90:93], v[66:69], v[2:17]
	v_add_f32_e32 v1, v209, v1
	v_add_f32_e32 v1, v211, v1
	v_add_f32_e32 v1, v97, v1
	v_add_f32_e32 v1, v220, v1
	v_add_f32_e32 v1, v96, v1
	v_add_f32_e32 v1, v94, v1
	v_add_f32_e32 v1, v95, v1
	v_cvt_pk_bf16_f32 v69, v86, v87
	v_cvt_pk_bf16_f32 v68, v215, v88
	v_cvt_pk_bf16_f32 v67, v214, v89
	v_cvt_pk_bf16_f32 v66, v212, v213
	v_add_f32_e32 v1, v212, v1
	v_add_f32_e32 v1, v213, v1
	s_waitcnt lgkmcnt(6)
	v_mfma_f32_32x32x16_bf16 v[50:65], v[70:73], v[66:69], v[50:65]
	v_add_f32_e32 v1, v214, v1
	v_add_f32_e32 v1, v89, v1
	v_add_f32_e32 v1, v215, v1
	v_add_f32_e32 v1, v88, v1
	v_add_f32_e32 v1, v86, v1
	v_add_f32_e32 v1, v87, v1
	v_add_f32_e32 v186, v186, v1
	s_waitcnt lgkmcnt(2)
	v_mfma_f32_32x32x16_bf16 v[34:49], v[74:77], v[66:69], v[34:49]
	s_waitcnt lgkmcnt(1)
	v_mfma_f32_32x32x16_bf16 v[18:33], v[78:81], v[66:69], v[18:33]
	s_waitcnt lgkmcnt(0)
	v_mfma_f32_32x32x16_bf16 v[2:17], v[82:85], v[66:69], v[2:17]
	s_mov_b32 s98, 0
	v_cmp_lt_f32_e32 vcc, 0x49800000, v1
	s_cbranch_vccz .Lsgphase4_12604
	s_nop 7
	s_nop 4
	v_mov_b32_e32 v250, v1
	v_mov_b32_e32 v251, v1
	s_nop 1
	v_permlane32_swap_b32_e32 v250, v251
	v_max_f32_e32 v250, v250, v251
	v_max_f32_e32 v250, 1.0, v250
	v_log_f32_e32 v250, v250
	s_nop 0
	v_sub_f32_e32 v252, 0, v250
	v_exp_f32_e32 v252, v252
	s_nop 0
	v_pk_mul_f32 v[64:65], v[64:65], v[252:253] op_sel_hi:[1,0]
	v_pk_mul_f32 v[62:63], v[62:63], v[252:253] op_sel_hi:[1,0]
	v_pk_mul_f32 v[60:61], v[60:61], v[252:253] op_sel_hi:[1,0]
	v_pk_mul_f32 v[58:59], v[58:59], v[252:253] op_sel_hi:[1,0]
	v_pk_mul_f32 v[56:57], v[56:57], v[252:253] op_sel_hi:[1,0]
	v_pk_mul_f32 v[54:55], v[54:55], v[252:253] op_sel_hi:[1,0]
	v_pk_mul_f32 v[52:53], v[52:53], v[252:253] op_sel_hi:[1,0]
	v_pk_mul_f32 v[50:51], v[50:51], v[252:253] op_sel_hi:[1,0]
	v_pk_mul_f32 v[48:49], v[48:49], v[252:253] op_sel_hi:[1,0]
	v_pk_mul_f32 v[46:47], v[46:47], v[252:253] op_sel_hi:[1,0]
	v_pk_mul_f32 v[44:45], v[44:45], v[252:253] op_sel_hi:[1,0]
	v_pk_mul_f32 v[42:43], v[42:43], v[252:253] op_sel_hi:[1,0]
	v_pk_mul_f32 v[40:41], v[40:41], v[252:253] op_sel_hi:[1,0]
	v_pk_mul_f32 v[38:39], v[38:39], v[252:253] op_sel_hi:[1,0]
	v_pk_mul_f32 v[36:37], v[36:37], v[252:253] op_sel_hi:[1,0]
	v_pk_mul_f32 v[34:35], v[34:35], v[252:253] op_sel_hi:[1,0]
	v_pk_mul_f32 v[32:33], v[32:33], v[252:253] op_sel_hi:[1,0]
	v_pk_mul_f32 v[30:31], v[30:31], v[252:253] op_sel_hi:[1,0]
	v_pk_mul_f32 v[28:29], v[28:29], v[252:253] op_sel_hi:[1,0]
	v_pk_mul_f32 v[26:27], v[26:27], v[252:253] op_sel_hi:[1,0]
	v_pk_mul_f32 v[24:25], v[24:25], v[252:253] op_sel_hi:[1,0]
	v_pk_mul_f32 v[22:23], v[22:23], v[252:253] op_sel_hi:[1,0]
	v_pk_mul_f32 v[20:21], v[20:21], v[252:253] op_sel_hi:[1,0]
	v_pk_mul_f32 v[18:19], v[18:19], v[252:253] op_sel_hi:[1,0]
	v_pk_mul_f32 v[16:17], v[16:17], v[252:253] op_sel_hi:[1,0]
	v_pk_mul_f32 v[14:15], v[14:15], v[252:253] op_sel_hi:[1,0]
	v_pk_mul_f32 v[12:13], v[12:13], v[252:253] op_sel_hi:[1,0]
	v_pk_mul_f32 v[10:11], v[10:11], v[252:253] op_sel_hi:[1,0]
	v_pk_mul_f32 v[8:9], v[8:9], v[252:253] op_sel_hi:[1,0]
	v_pk_mul_f32 v[6:7], v[6:7], v[252:253] op_sel_hi:[1,0]
	v_pk_mul_f32 v[4:5], v[4:5], v[252:253] op_sel_hi:[1,0]
	v_pk_mul_f32 v[2:3], v[2:3], v[252:253] op_sel_hi:[1,0]
	v_mul_f32_e32 v186, v186, v252
	v_sub_f32_e32 v248, v248, v250
	v_xor_b32_e32 v206, 0x80000000, v248
	v_mov_b32_e32 v232, v248
	v_mov_b32_e32 v233, v248
	v_mov_b32_e32 v234, v248
	v_mov_b32_e32 v235, v248
	v_mov_b32_e32 v236, v248
	v_mov_b32_e32 v237, v248
	v_mov_b32_e32 v238, v248
	v_mov_b32_e32 v239, v248
	v_mov_b32_e32 v240, v248
	v_mov_b32_e32 v241, v248
	v_mov_b32_e32 v242, v248
	v_mov_b32_e32 v243, v248
	v_mov_b32_e32 v244, v248
	v_mov_b32_e32 v245, v248
	v_mov_b32_e32 v246, v248
	v_mov_b32_e32 v247, v248
.Lsgphase4_12604:
	s_cbranch_scc1 .LBB0_1207

.LBB0_1205:
	s_nop 8
	s_cmp_eq_u32 s98, 0
	s_cbranch_scc1 .LBB0_1200
	v_max3_f32 v1, v82, s48, v83
	v_max3_f32 v1, v1, v84, v85
	v_max3_f32 v1, v1, v86, v87
	v_max3_f32 v1, v1, v88, v89
	v_max3_f32 v1, v1, v90, v91
	v_max3_f32 v1, v1, v92, v93
	v_max3_f32 v1, v1, v94, v95
	v_max3_f32 v1, v1, v96, v97
	v_max3_f32 v1, v1, v66, v67
	v_max3_f32 v1, v1, v68, v69
	v_max3_f32 v1, v1, v70, v71
	v_max3_f32 v1, v1, v72, v73
	v_max3_f32 v1, v1, v74, v75
	v_max3_f32 v1, v1, v76, v77
	v_max3_f32 v1, v1, v78, v79
	v_max3_f32 v1, v1, v80, v81
	ds_bpermute_b32 v207, v180, v1
	s_waitcnt lgkmcnt(0)
	v_max_f32_e32 v207, v207, v207
	v_max_f32_e32 v1, v1, v207
	v_add_f32_e32 v207, 0x41000000, v249
	v_cmp_gt_f32_e32 vcc, v1, v207
	s_cbranch_vccz .LBB0_1200
	v_max_f32_e32 v1, v1, v1
	v_max_f32_e32 v250, v249, v249
	v_max_f32_e32 v250, v250, v1
	v_sub_f32_e32 v251, v250, v248
	v_sub_f32_e32 v206, v249, v250
	v_exp_f32_e32 v206, v206
	s_nop 0
	v_pk_mul_f32 v[64:65], v[64:65], v[206:207] op_sel_hi:[1,0]
	v_pk_mul_f32 v[62:63], v[62:63], v[206:207] op_sel_hi:[1,0]
	v_pk_mul_f32 v[60:61], v[60:61], v[206:207] op_sel_hi:[1,0]
	v_pk_mul_f32 v[58:59], v[58:59], v[206:207] op_sel_hi:[1,0]
	v_pk_mul_f32 v[56:57], v[56:57], v[206:207] op_sel_hi:[1,0]
	v_pk_mul_f32 v[54:55], v[54:55], v[206:207] op_sel_hi:[1,0]
	v_pk_mul_f32 v[52:53], v[52:53], v[206:207] op_sel_hi:[1,0]
	v_pk_mul_f32 v[50:51], v[50:51], v[206:207] op_sel_hi:[1,0]
	v_pk_mul_f32 v[48:49], v[48:49], v[206:207] op_sel_hi:[1,0]
	v_pk_mul_f32 v[46:47], v[46:47], v[206:207] op_sel_hi:[1,0]
	v_pk_mul_f32 v[44:45], v[44:45], v[206:207] op_sel_hi:[1,0]
	v_pk_mul_f32 v[42:43], v[42:43], v[206:207] op_sel_hi:[1,0]
	v_pk_mul_f32 v[40:41], v[40:41], v[206:207] op_sel_hi:[1,0]
	v_pk_mul_f32 v[38:39], v[38:39], v[206:207] op_sel_hi:[1,0]
	v_pk_mul_f32 v[36:37], v[36:37], v[206:207] op_sel_hi:[1,0]
	v_pk_mul_f32 v[34:35], v[34:35], v[206:207] op_sel_hi:[1,0]
	v_pk_mul_f32 v[32:33], v[32:33], v[206:207] op_sel_hi:[1,0]
	v_pk_mul_f32 v[30:31], v[30:31], v[206:207] op_sel_hi:[1,0]
	v_pk_mul_f32 v[28:29], v[28:29], v[206:207] op_sel_hi:[1,0]
	v_pk_mul_f32 v[26:27], v[26:27], v[206:207] op_sel_hi:[1,0]
	v_pk_mul_f32 v[24:25], v[24:25], v[206:207] op_sel_hi:[1,0]
	v_pk_mul_f32 v[22:23], v[22:23], v[206:207] op_sel_hi:[1,0]
	v_pk_mul_f32 v[20:21], v[20:21], v[206:207] op_sel_hi:[1,0]
	v_pk_mul_f32 v[18:19], v[18:19], v[206:207] op_sel_hi:[1,0]
	v_pk_mul_f32 v[16:17], v[16:17], v[206:207] op_sel_hi:[1,0]
	v_pk_mul_f32 v[14:15], v[14:15], v[206:207] op_sel_hi:[1,0]
	v_pk_mul_f32 v[12:13], v[12:13], v[206:207] op_sel_hi:[1,0]
	v_pk_mul_f32 v[10:11], v[10:11], v[206:207] op_sel_hi:[1,0]
	v_pk_mul_f32 v[8:9], v[8:9], v[206:207] op_sel_hi:[1,0]
	v_pk_mul_f32 v[6:7], v[6:7], v[206:207] op_sel_hi:[1,0]
	v_pk_mul_f32 v[4:5], v[4:5], v[206:207] op_sel_hi:[1,0]
	v_pk_mul_f32 v[2:3], v[2:3], v[206:207] op_sel_hi:[1,0]
	v_mul_f32_e32 v186, v186, v206
	v_mov_b32_e32 v206, v251
	v_xor_b32_e32 v250, 0x80000000, v251
	v_cmp_lt_f32_e32 vcc, 0xf0a18f08, v251
	s_nop 1
	v_cndmask_b32_e32 v250, 0, v250, vcc
	v_add_f32_e32 v249, v251, v250
	v_sub_f32_e32 v251, v250, v248
	v_mov_b32_e32 v248, v250
	v_add_f32_e32 v66, v251, v66
	v_add_f32_e32 v67, v251, v67
	v_add_f32_e32 v68, v251, v68
	v_add_f32_e32 v69, v251, v69
	v_add_f32_e32 v70, v251, v70
	v_add_f32_e32 v71, v251, v71
	v_add_f32_e32 v72, v251, v72
	v_add_f32_e32 v73, v251, v73
	v_add_f32_e32 v74, v251, v74
	v_add_f32_e32 v75, v251, v75
	v_add_f32_e32 v76, v251, v76
	v_add_f32_e32 v77, v251, v77
	v_add_f32_e32 v78, v251, v78
	v_add_f32_e32 v79, v251, v79
	v_add_f32_e32 v80, v251, v80
	v_add_f32_e32 v81, v251, v81
	v_add_f32_e32 v82, v251, v82
	v_add_f32_e32 v83, v251, v83
	v_add_f32_e32 v84, v251, v84
	v_add_f32_e32 v85, v251, v85
	v_add_f32_e32 v86, v251, v86
	v_add_f32_e32 v87, v251, v87
	v_add_f32_e32 v88, v251, v88
	v_add_f32_e32 v89, v251, v89
	v_add_f32_e32 v90, v251, v90
	v_add_f32_e32 v91, v251, v91
	v_add_f32_e32 v92, v251, v92
	v_add_f32_e32 v93, v251, v93
	v_add_f32_e32 v94, v251, v94
	v_add_f32_e32 v95, v251, v95
	v_add_f32_e32 v96, v251, v96
	v_add_f32_e32 v97, v251, v97
	v_mov_b32_e32 v232, v250
	v_mov_b32_e32 v233, v250
	v_mov_b32_e32 v234, v250
	v_mov_b32_e32 v235, v250
	v_mov_b32_e32 v236, v250
	v_mov_b32_e32 v237, v250
	v_mov_b32_e32 v238, v250
	v_mov_b32_e32 v239, v250
	v_mov_b32_e32 v240, v250
	v_mov_b32_e32 v241, v250
	v_mov_b32_e32 v242, v250
	v_mov_b32_e32 v243, v250
	v_mov_b32_e32 v244, v250
	v_mov_b32_e32 v245, v250
	v_mov_b32_e32 v246, v250
	v_mov_b32_e32 v247, v250
	v_cndmask_b32_e32 v206, 0, v206, vcc
	s_branch .LBB0_1200
